# LayerNorm row loop: counted vmcnt at the loop top (8/16/48/56 by which outputs exist) instead of vmcnt(0), so the previous row's stores are not drained every row
# baseline (speedup 1.0000x reference)
; __device__ __forceinline__ void ln_load16(const void* src, size_t row, int lane, h16x4 (&t)[8]) {
;     const h16x4* sp = (const h16x4*)((const h16*)src + row * DM);
; #pragma unroll
;     for (int i = 0; i < 8; ++i) t[i] = sp[i * 64 + lane];
; }
; template <bool LN>
; __device__ __forceinline__ void ln_phase(const void* src, const float* g, const float* bt, float* xout, h16* xh, const float* mu, h16* mix) {
;     ...
;         h16x4 raw[8], rawn[8];
;         if (LN) ln_load16(src, t0, lane, raw);
.LBB0_121:
	v_lshlrev_b64 v[18:19], 15, v[70:71]
	v_lshl_add_u64 v[18:19], v[92:93], 0, v[18:19]
	global_load_dwordx2 v[194:195], v[18:19], off
	global_load_dwordx2 v[196:197], v[18:19], off offset:512
	global_load_dwordx2 v[198:199], v[18:19], off offset:1024
	global_load_dwordx2 v[200:201], v[18:19], off offset:1536
	global_load_dwordx2 v[202:203], v[18:19], off offset:2048
	global_load_dwordx2 v[204:205], v[18:19], off offset:2560
	global_load_dwordx2 v[206:207], v[18:19], off offset:3072
	global_load_dwordx2 v[220:221], v[18:19], off offset:3584
	v_lshlrev_b64 v[190:191], 3, v[70:71]
	s_mov_b64 s[22:23], 0
	s_mov_b32 s26, 1
	v_mov_b64_e32 v[192:193], v[186:187]
	s_waitcnt vmcnt(0)
	s_branch .LBB0_124

; __device__ __forceinline__ float wave_sum(float x) { x = row16_sum(x); x += __shfl_xor(x, 16); x += __shfl_xor(x, 32); return x; }
; __device__ __forceinline__ void ln_apply16(const h16x4 (&t)[8], int lane, const float* g, const float* bt, f32x4 (&v)[8]) {
; #pragma unroll
;     for (int i = 0; i < 8; ++i) v[i] = (f32x4){(float)t[i][0], (float)t[i][1], (float)t[i][2], (float)t[i][3]};
;     float s = 0.f;
; #pragma unroll
;     for (int i = 0; i < 8; ++i) s += (v[i][0] + v[i][1]) + (v[i][2] + v[i][3]);
;     const float mean = wave_sum(s) * (1.0f / DM);
; template <bool LN>
; __device__ __forceinline__ void ln_phase(const void* src, const float* g, const float* bt, float* xout, h16* xh, const float* mu, h16* mix) {
;     ...
;         for (int r = 0; r < 8; ++r) {
;             const size_t row = t0 + r;
;             asm volatile("" ::: "memory");
;             if (LN) {
;                 ln_load16(src, t0 + (r < 7 ? r + 1 : 7), lane, rawn);
;                 ln_apply16(raw, lane, g, bt, cur);
; #pragma unroll
;                 for (int i = 0; i < 8; ++i) raw[i] = rawn[i];
.LBB0_124:
	v_mov_b64_e32 v[64:65], v[4:5]
	v_mov_b64_e32 v[56:57], v[8:9]
	v_mov_b64_e32 v[52:53], v[12:13]
	v_mov_b64_e32 v[48:49], v[16:17]
	v_mov_b64_e32 v[44:45], v[24:25]
	v_mov_b64_e32 v[40:41], v[32:33]
	v_mov_b64_e32 v[26:27], v[34:35]
	v_mov_b64_e32 v[18:19], v[58:59]
	v_mov_b64_e32 v[62:63], v[2:3]
	v_mov_b64_e32 v[54:55], v[6:7]
	v_mov_b64_e32 v[50:51], v[10:11]
	v_mov_b64_e32 v[46:47], v[14:15]
	v_mov_b64_e32 v[42:43], v[22:23]
	v_mov_b64_e32 v[38:39], v[30:31]
	v_mov_b64_e32 v[28:29], v[36:37]
	v_mov_b64_e32 v[20:21], v[60:61]
	s_cmpk_lg_i32 s22, 0x7000
	s_cselect_b32 s24, s26, 7
	v_lshl_add_u64 v[2:3], v[190:191], 0, s[24:25]
	v_lshlrev_b64 v[2:3], 12, v[2:3]
	s_cmp_lg_u64 s[44:45], 0
	s_cselect_b32 s100, 8, 0
	s_cmp_lg_u64 s[46:47], 0
	s_cselect_b32 s101, 8, 0
	s_add_i32 s100, s100, s101
	s_cmp_eq_u64 s[38:39], 0
	s_cselect_b32 s101, 48, 0
	s_add_i32 s100, s100, s101
	s_cmp_ge_u32 s100, 56
	s_cbranch_scc1 .Lln_w56
	s_cmp_ge_u32 s100, 48
	s_cbranch_scc1 .Lln_w48
	s_cmp_ge_u32 s100, 16
	s_cbranch_scc1 .Lln_w16
	s_cmp_ge_u32 s100, 8
	s_cbranch_scc1 .Lln_w8
	s_waitcnt vmcnt(0)
	s_branch .Lln_wd
.Lln_w56:
	s_waitcnt vmcnt(56)
	s_branch .Lln_wd
.Lln_w48:
	s_waitcnt vmcnt(48)
	s_branch .Lln_wd
.Lln_w16:
	s_waitcnt vmcnt(16)
	s_branch .Lln_wd
.Lln_w8:
	s_waitcnt vmcnt(8)
.Lln_wd:
	v_mov_b64_e32 v[4:5], v[194:195]
	v_mov_b64_e32 v[8:9], v[196:197]
	v_lshl_add_u64 v[2:3], v[92:93], 0, v[2:3]
	v_mov_b64_e32 v[14:15], v[198:199]
	v_mov_b64_e32 v[22:23], v[200:201]
	v_mov_b64_e32 v[24:25], v[202:203]
	v_mov_b64_e32 v[34:35], v[204:205]
	v_mov_b64_e32 v[60:61], v[206:207]
	v_mov_b64_e32 v[58:59], v[220:221]
	global_load_dwordx2 v[194:195], v[2:3], off
	global_load_dwordx2 v[196:197], v[2:3], off offset:512
	global_load_dwordx2 v[198:199], v[2:3], off offset:1024
	global_load_dwordx2 v[200:201], v[2:3], off offset:1536
	global_load_dwordx2 v[202:203], v[2:3], off offset:2048
	global_load_dwordx2 v[204:205], v[2:3], off offset:2560
	global_load_dwordx2 v[206:207], v[2:3], off offset:3072
	global_load_dwordx2 v[220:221], v[2:3], off offset:3584
	v_cvt_f32_f16_sdwa v3, v4 dst_sel:DWORD dst_unused:UNUSED_PAD src0_sel:WORD_1
	v_cvt_f32_f16_e32 v7, v4
	v_cvt_f32_f16_sdwa v11, v5 dst_sel:DWORD dst_unused:UNUSED_PAD src0_sel:WORD_1
	v_cvt_f32_f16_e32 v13, v5
	v_cvt_f32_f16_sdwa v2, v8 dst_sel:DWORD dst_unused:UNUSED_PAD src0_sel:WORD_1
	v_cvt_f32_f16_e32 v6, v8
	v_cvt_f32_f16_sdwa v10, v9 dst_sel:DWORD dst_unused:UNUSED_PAD src0_sel:WORD_1
	v_cvt_f32_f16_e32 v12, v9
	v_cvt_f32_f16_sdwa v16, v14 dst_sel:DWORD dst_unused:UNUSED_PAD src0_sel:WORD_1
	v_cvt_f32_f16_e32 v30, v14
	v_cvt_f32_f16_sdwa v17, v15 dst_sel:DWORD dst_unused:UNUSED_PAD src0_sel:WORD_1
	v_cvt_f32_f16_e32 v31, v15
	v_pk_add_f32 v[2:3], v[6:7], v[2:3]
	v_pk_add_f32 v[6:7], v[12:13], v[10:11]
	v_cvt_f32_f16_sdwa v0, v22 dst_sel:DWORD dst_unused:UNUSED_PAD src0_sel:WORD_1
	v_cvt_f32_f16_e32 v33, v22
	v_cvt_f32_f16_sdwa v69, v23 dst_sel:DWORD dst_unused:UNUSED_PAD src0_sel:WORD_1
	v_cvt_f32_f16_e32 v71, v23
	v_pk_add_f32 v[2:3], v[2:3], v[6:7]
	v_cvt_f32_f16_sdwa v32, v24 dst_sel:DWORD dst_unused:UNUSED_PAD src0_sel:WORD_1
	v_cvt_f32_f16_e32 v36, v24
	v_cvt_f32_f16_sdwa v66, v25 dst_sel:DWORD dst_unused:UNUSED_PAD src0_sel:WORD_1
	v_cvt_f32_f16_e32 v68, v25
	v_add_f32_e32 v3, 0, v3
	v_cvt_f32_f16_sdwa v212, v34 dst_sel:DWORD dst_unused:UNUSED_PAD src0_sel:WORD_1
	v_cvt_f32_f16_e32 v214, v34
	v_cvt_f32_f16_sdwa v213, v35 dst_sel:DWORD dst_unused:UNUSED_PAD src0_sel:WORD_1
	v_cvt_f32_f16_e32 v215, v35
	v_add_f32_e32 v67, v2, v3
	v_pk_add_f32 v[2:3], v[30:31], v[16:17]
	v_cvt_f32_f16_sdwa v217, v60 dst_sel:DWORD dst_unused:UNUSED_PAD src0_sel:WORD_1
	v_pk_add_f32 v[2:3], v[2:3], v[2:3] op_sel_hi:[0,1]
	v_cvt_f32_f16_e32 v223, v60
	v_cvt_f32_f16_sdwa v225, v61 dst_sel:DWORD dst_unused:UNUSED_PAD src0_sel:WORD_1
	v_cvt_f32_f16_e32 v227, v61
	v_add_f32_e32 v37, v33, v0
	v_add_f32_e32 v33, v71, v69
	v_mov_b32_e32 v69, v3
	v_cvt_f32_f16_sdwa v216, v58 dst_sel:DWORD dst_unused:UNUSED_PAD src0_sel:WORD_1
	v_cvt_f32_f16_e32 v222, v58
	v_cvt_f32_f16_sdwa v224, v59 dst_sel:DWORD dst_unused:UNUSED_PAD src0_sel:WORD_1
	v_cvt_f32_f16_e32 v226, v59
	v_pk_add_f32 v[6:7], v[36:37], v[32:33]
	v_pk_add_f32 v[2:3], v[68:69], v[66:67]
	v_add_f32_e32 v223, v223, v217
	v_pk_add_f32 v[2:3], v[6:7], v[2:3]
	v_pk_add_f32 v[6:7], v[214:215], v[212:213]
	v_pk_add_f32 v[2:3], v[2:3], v[2:3] op_sel_hi:[0,1]
	v_pk_add_f32 v[6:7], v[6:7], v[6:7] op_sel_hi:[0,1]
	v_add_f32_e32 v217, v227, v225
	v_mov_b32_e32 v227, v7
	v_mov_b32_e32 v225, v3
	v_pk_add_f32 v[10:11], v[222:223], v[216:217]
	v_pk_add_f32 v[2:3], v[226:227], v[224:225]
	s_nop 0
	v_pk_add_f32 v[2:3], v[10:11], v[2:3]
	s_nop 0
	v_add_f32_e32 v0, v2, v3
	v_and_b32_e32 v3, 64, v246
	v_xor_b32_e32 v2, 16, v246
	v_add_f32_dpp v0, v0, v0 quad_perm:[1,0,3,2] row_mask:0xf bank_mask:0xf bound_ctrl:1
	v_add_u32_e32 v3, 64, v3
	v_cmp_lt_i32_e32 vcc, v2, v3
	v_add_f32_dpp v0, v0, v0 quad_perm:[2,3,0,1] row_mask:0xf bank_mask:0xf bound_ctrl:1
	s_nop 0
	v_cndmask_b32_e32 v2, v246, v2, vcc
	v_add_f32_dpp v0, v0, v0 row_half_mirror row_mask:0xf bank_mask:0xf bound_ctrl:1
	v_lshlrev_b32_e32 v71, 2, v2
	s_nop 0
	v_add_f32_dpp v0, v0, v0 row_mirror row_mask:0xf bank_mask:0xf bound_ctrl:1
	ds_bpermute_b32 v2, v71, v0
	s_waitcnt lgkmcnt(0)
	v_add_f32_e32 v0, v0, v2
	v_xor_b32_e32 v2, 32, v246
	v_cmp_lt_i32_e32 vcc, v2, v3
	s_nop 1
	v_cndmask_b32_e32 v2, v246, v2, vcc
	v_lshlrev_b32_e32 v214, 2, v2
	ds_bpermute_b32 v2, v214, v0
	s_waitcnt lgkmcnt(0)
; __device__ __forceinline__ float wave_sum(float x) { x = row16_sum(x); x += __shfl_xor(x, 16); x += __shfl_xor(x, 32); return x; }
; __device__ __forceinline__ void ln_apply16(const h16x4 (&t)[8], int lane, const float* g, const float* bt, f32x4 (&v)[8]) {
;     ...
;     const float mean = wave_sum(s) * (1.0f / DM);
;     float q = 0.f;
; #pragma unroll
;     for (int i = 0; i < 8; ++i) { v[i] = v[i] - mean; q += (v[i][0] * v[i][0] + v[i][1] * v[i][1]) + (v[i][2] * v[i][2] + v[i][3] * v[i][3]); }
;     const float rstd = rsqrtf(wave_sum(q) * (1.0f / DM) + 1e-5f);
	v_add_f32_e32 v215, v0, v2
	v_fma_mix_f32 v3, v215, s59, v5 op_sel:[0,0,1] op_sel_hi:[0,0,1]
	v_fma_mix_f32 v2, v215, s59, v5 op_sel_hi:[0,0,1]
	v_fma_mix_f32 v5, v215, s59, v4 op_sel:[0,0,1] op_sel_hi:[0,0,1]
	v_fma_mix_f32 v7, v215, s59, v9 op_sel:[0,0,1] op_sel_hi:[0,0,1]
	v_fma_mix_f32 v6, v215, s59, v9 op_sel_hi:[0,0,1]
	v_fma_mix_f32 v9, v215, s59, v8 op_sel:[0,0,1] op_sel_hi:[0,0,1]
	v_fma_mix_f32 v4, v215, s59, v4 op_sel_hi:[0,0,1]
	v_fma_mix_f32 v8, v215, s59, v8 op_sel_hi:[0,0,1]
	v_mov_b32_e32 v12, v5
	v_mov_b32_e32 v13, v9
	v_mov_b32_e32 v10, v4
	v_mov_b32_e32 v11, v8
	v_pk_mul_f32 v[12:13], v[12:13], v[12:13]
	v_mov_b32_e32 v16, v3
	v_mov_b32_e32 v17, v7
	v_pk_fma_f32 v[10:11], v[10:11], v[10:11], v[12:13]
	v_mov_b32_e32 v12, v2
	v_mov_b32_e32 v13, v6
	v_pk_mul_f32 v[16:17], v[16:17], v[16:17]
	v_fma_mix_f32 v223, v215, s59, v59 op_sel:[0,0,1] op_sel_hi:[0,0,1]
	v_pk_fma_f32 v[12:13], v[12:13], v[12:13], v[16:17]
	v_fma_mix_f32 v222, v215, s59, v59 op_sel_hi:[0,0,1]
	v_pk_add_f32 v[10:11], v[10:11], v[12:13]
	v_fma_mix_f32 v13, v215, s59, v15 op_sel:[0,0,1] op_sel_hi:[0,0,1]
	v_pk_add_f32 v[30:31], v[10:11], v[10:11] op_sel_hi:[0,1]
	v_fma_mix_f32 v11, v215, s59, v14 op_sel:[0,0,1] op_sel_hi:[0,0,1]
	v_fma_mix_f32 v10, v215, s59, v14 op_sel_hi:[0,0,1]
	v_fma_mix_f32 v12, v215, s59, v15 op_sel_hi:[0,0,1]
	v_pk_mul_f32 v[14:15], v[12:13], v[12:13]
	v_pk_mul_f32 v[16:17], v[10:11], v[10:11]
	v_fma_mix_f32 v225, v215, s59, v58 op_sel:[0,0,1] op_sel_hi:[0,0,1]
	v_pk_mov_b32 v[32:33], v[16:17], v[14:15] op_sel:[1,0]
	v_mov_b32_e32 v17, v15
	v_pk_add_f32 v[14:15], v[32:33], v[16:17]
	v_fma_mix_f32 v16, v215, s59, v23 op_sel_hi:[0,0,1]
	v_pk_add_f32 v[32:33], v[14:15], v[14:15] op_sel_hi:[0,1]
	v_fma_mix_f32 v14, v215, s59, v22 op_sel_hi:[0,0,1]
	v_fma_mix_f32 v15, v215, s59, v22 op_sel:[0,0,1] op_sel_hi:[0,0,1]
	v_mul_f32_e32 v0, v14, v14
	v_fma_mix_f32 v17, v215, s59, v23 op_sel:[0,0,1] op_sel_hi:[0,0,1]
	v_pk_fma_f32 v[36:37], v[14:15], v[14:15], v[0:1] op_sel_hi:[1,1,0]
	v_mul_f32_e32 v0, v16, v16
	v_pk_fma_f32 v[66:67], v[16:17], v[16:17], v[0:1] op_sel_hi:[1,1,0]
	v_fma_mix_f32 v23, v215, s59, v25 op_sel:[0,0,1] op_sel_hi:[0,0,1]
	v_fma_mix_f32 v22, v215, s59, v25 op_sel_hi:[0,0,1]
	v_fma_mix_f32 v25, v215, s59, v24 op_sel:[0,0,1] op_sel_hi:[0,0,1]
	v_fma_mix_f32 v24, v215, s59, v24 op_sel_hi:[0,0,1]
	v_mul_f32_e32 v36, v24, v24
	v_mul_f32_e32 v66, v25, v25
	v_mul_f32_e32 v32, v22, v22
	v_mul_f32_e32 v30, v23, v23
	v_pk_add_f32 v[36:37], v[36:37], v[66:67]
	v_pk_add_f32 v[30:31], v[32:33], v[30:31]
	v_fma_mix_f32 v33, v215, s59, v35 op_sel:[0,0,1] op_sel_hi:[0,0,1]
	v_pk_add_f32 v[30:31], v[36:37], v[30:31]
	v_fma_mix_f32 v32, v215, s59, v35 op_sel_hi:[0,0,1]
	v_pk_add_f32 v[66:67], v[30:31], v[30:31] op_sel_hi:[0,1]
	v_fma_mix_f32 v31, v215, s59, v34 op_sel:[0,0,1] op_sel_hi:[0,0,1]
	v_fma_mix_f32 v30, v215, s59, v34 op_sel_hi:[0,0,1]
	v_pk_mul_f32 v[34:35], v[32:33], v[32:33]
	v_pk_mul_f32 v[36:37], v[30:31], v[30:31]
	v_fma_mix_f32 v224, v215, s59, v58 op_sel_hi:[0,0,1]
	v_pk_mov_b32 v[68:69], v[36:37], v[34:35] op_sel:[1,0]
	v_mov_b32_e32 v37, v35
	v_pk_add_f32 v[34:35], v[68:69], v[36:37]
	v_fma_mix_f32 v36, v215, s59, v61 op_sel_hi:[0,0,1]
	v_pk_add_f32 v[68:69], v[34:35], v[34:35] op_sel_hi:[0,1]
	v_fma_mix_f32 v34, v215, s59, v60 op_sel_hi:[0,0,1]
	v_fma_mix_f32 v35, v215, s59, v60 op_sel:[0,0,1] op_sel_hi:[0,0,1]
	v_mul_f32_e32 v0, v34, v34
	v_fma_mix_f32 v37, v215, s59, v61 op_sel:[0,0,1] op_sel_hi:[0,0,1]
	v_pk_fma_f32 v[60:61], v[34:35], v[34:35], v[0:1] op_sel_hi:[1,1,0]
	v_mul_f32_e32 v0, v36, v36
	v_pk_fma_f32 v[212:213], v[36:37], v[36:37], v[0:1] op_sel_hi:[1,1,0]
	v_mul_f32_e32 v60, v224, v224
	v_mul_f32_e32 v212, v225, v225
	v_mul_f32_e32 v68, v222, v222
	v_mul_f32_e32 v66, v223, v223
	v_pk_add_f32 v[58:59], v[60:61], v[212:213]
	v_pk_add_f32 v[60:61], v[68:69], v[66:67]
	s_nop 0
	v_pk_add_f32 v[58:59], v[58:59], v[60:61]
	s_nop 0
	v_add_f32_e32 v0, v58, v59
	s_nop 1
	v_add_f32_dpp v0, v0, v0 quad_perm:[1,0,3,2] row_mask:0xf bank_mask:0xf bound_ctrl:1
	s_nop 1
	v_add_f32_dpp v0, v0, v0 quad_perm:[2,3,0,1] row_mask:0xf bank_mask:0xf bound_ctrl:1
	s_nop 1
	v_add_f32_dpp v0, v0, v0 row_half_mirror row_mask:0xf bank_mask:0xf bound_ctrl:1
	s_nop 1
	v_add_f32_dpp v0, v0, v0 row_mirror row_mask:0xf bank_mask:0xf bound_ctrl:1
	ds_bpermute_b32 v58, v71, v0
	s_waitcnt lgkmcnt(0)
; __device__ __forceinline__ float wave_sum(float x) { x = row16_sum(x); x += __shfl_xor(x, 16); x += __shfl_xor(x, 32); return x; }
; __device__ __forceinline__ void ln_apply16(const h16x4 (&t)[8], int lane, const float* g, const float* bt, f32x4 (&v)[8]) {
;     ...
;     const float rstd = rsqrtf(wave_sum(q) * (1.0f / DM) + 1e-5f);
; #pragma unroll
;     for (int i = 0; i < 8; ++i) { const f32x4 gg = ((const f32x4*)g)[i * 64 + lane], bb = ((const f32x4*)bt)[i * 64 + lane]; v[i] = v[i] * rstd * gg + bb; }
; template <bool LN>
; __device__ __forceinline__ void ln_phase(const void* src, const float* g, const float* bt, float* xout, h16* xh, const float* mu, h16* mix) {
;     ...
;             if (xout) {
; #pragma unroll
;                 for (int i = 0; i < 8; ++i) ((f32x4*)(xout + row * DM))[i * 64 + lane] = cur[i];
;             }
	v_add_f32_e32 v0, v0, v58
	ds_bpermute_b32 v58, v214, v0
	s_waitcnt lgkmcnt(0)
	v_add_f32_e32 v0, v0, v58
	v_fmamk_f32 v0, v0, 0x3a000000, v242
	v_cmp_gt_f32_e32 vcc, s28, v0
	v_mul_f32_e32 v58, 0x4b800000, v0
	s_nop 0
	v_cndmask_b32_e32 v0, v0, v58, vcc
	v_rsq_f32_e32 v0, v0
	s_nop 0
	v_mul_f32_e32 v58, 0x45800000, v0
	v_cndmask_b32_e32 v0, v0, v58, vcc
	ds_read_b128 v[58:61], v230 offset:49152
	ds_read_b128 v[66:69], v230 offset:57344
	v_pk_mul_f32 v[212:213], v[4:5], v[0:1] op_sel_hi:[1,0]
	v_pk_mul_f32 v[2:3], v[2:3], v[0:1] op_sel_hi:[1,0]
	v_pk_mul_f32 v[6:7], v[6:7], v[0:1] op_sel_hi:[1,0]
	v_pk_mul_f32 v[10:11], v[10:11], v[0:1] op_sel_hi:[1,0]
	v_pk_mul_f32 v[12:13], v[12:13], v[0:1] op_sel_hi:[1,0]
	v_pk_mul_f32 v[14:15], v[14:15], v[0:1] op_sel_hi:[1,0]
	v_pk_mul_f32 v[16:17], v[16:17], v[0:1] op_sel_hi:[1,0]
	v_pk_mul_f32 v[22:23], v[22:23], v[0:1] op_sel_hi:[1,0]
	v_pk_mul_f32 v[30:31], v[30:31], v[0:1] op_sel_hi:[1,0]
	v_pk_mul_f32 v[32:33], v[32:33], v[0:1] op_sel_hi:[1,0]
	v_pk_mul_f32 v[34:35], v[34:35], v[0:1] op_sel_hi:[1,0]
	v_pk_mul_f32 v[36:37], v[36:37], v[0:1] op_sel_hi:[1,0]
	v_pk_mul_f32 v[214:215], v[222:223], v[0:1] op_sel_hi:[1,0]
	s_andn2_b64 vcc, exec, s[44:45]
	s_waitcnt lgkmcnt(0)
	v_pk_fma_f32 v[4:5], v[60:61], v[2:3], v[68:69]
	v_pk_fma_f32 v[2:3], v[58:59], v[212:213], v[66:67]
	ds_read_b128 v[58:61], v230 offset:50176
	ds_read_b128 v[66:69], v230 offset:58368
	v_pk_mul_f32 v[212:213], v[8:9], v[0:1] op_sel_hi:[1,0]
	s_waitcnt lgkmcnt(0)
	v_pk_fma_f32 v[8:9], v[60:61], v[6:7], v[68:69]
	v_pk_fma_f32 v[6:7], v[58:59], v[212:213], v[66:67]
	ds_read_b128 v[58:61], v230 offset:51200
	ds_read_b128 v[66:69], v230 offset:59392
	v_pk_mul_f32 v[212:213], v[24:25], v[0:1] op_sel_hi:[1,0]
	s_waitcnt lgkmcnt(0)
	v_pk_fma_f32 v[12:13], v[60:61], v[12:13], v[68:69]
	v_pk_fma_f32 v[10:11], v[58:59], v[10:11], v[66:67]
	ds_read_b128 v[58:61], v230 offset:52224
	ds_read_b128 v[66:69], v230 offset:60416
	s_waitcnt lgkmcnt(0)
	v_pk_fma_f32 v[16:17], v[60:61], v[16:17], v[68:69]
	v_pk_fma_f32 v[14:15], v[58:59], v[14:15], v[66:67]
	ds_read_b128 v[58:61], v230 offset:53248
	ds_read_b128 v[66:69], v230 offset:61440
	s_waitcnt lgkmcnt(0)
	v_pk_fma_f32 v[24:25], v[60:61], v[22:23], v[68:69]
	v_pk_fma_f32 v[22:23], v[58:59], v[212:213], v[66:67]
	ds_read_b128 v[58:61], v230 offset:54272
	ds_read_b128 v[66:69], v230 offset:62464
	v_pk_mul_f32 v[212:213], v[224:225], v[0:1] op_sel_hi:[1,0]
	s_waitcnt lgkmcnt(0)
	v_pk_fma_f32 v[32:33], v[60:61], v[32:33], v[68:69]
	v_pk_fma_f32 v[30:31], v[58:59], v[30:31], v[66:67]
	ds_read_b128 v[58:61], v230 offset:55296
	ds_read_b128 v[66:69], v230 offset:63488
	s_waitcnt lgkmcnt(0)
	v_pk_fma_f32 v[36:37], v[60:61], v[36:37], v[68:69]
	v_pk_fma_f32 v[34:35], v[58:59], v[34:35], v[66:67]
	ds_read_b128 v[58:61], v230 offset:56320
	ds_read_b128 v[66:69], v230 offset:64512
	s_waitcnt lgkmcnt(0)
	v_pk_fma_f32 v[60:61], v[60:61], v[214:215], v[68:69]
	v_pk_fma_f32 v[58:59], v[58:59], v[212:213], v[66:67]
	s_cbranch_vccnz .LBB0_126
	global_store_dwordx4 v[192:193], v[2:5], off offset:-4096
	global_store_dwordx4 v[192:193], v[6:9], off offset:-3072
	global_store_dwordx4 v[192:193], v[10:13], off offset:-2048
	global_store_dwordx4 v[192:193], v[14:17], off offset:-1024
	global_store_dwordx4 v[192:193], v[22:25], off
	global_store_dwordx4 v[192:193], v[30:33], off offset:1024
	global_store_dwordx4 v[192:193], v[34:37], off offset:2048
	global_store_dwordx4 v[192:193], v[58:61], off offset:3072
